# in-proj parameter-table fill de-serialised (14 loads in flight, one wait) on top of stagger0 + S1 MFMA removal
# speedup vs baseline: 1.0172x; 1.0097x over previous
.LBB0_203:
	s_cmp_lt_i32 s58, 2
	s_cselect_b64 s[0:1], -1, 0
	s_add_u32 s72, s70, 0xc000000
	s_addc_u32 s73, s71, 0
	s_add_u32 s78, s70, 0x12000000
	s_addc_u32 s79, s71, 0
	s_add_u32 s2, s70, 0x1a000000
	s_addc_u32 s3, s71, 0
	s_add_u32 s80, s70, 0x1a800000
	s_addc_u32 s81, s71, 0
	s_add_u32 s74, s70, 0x22000000
	s_addc_u32 s75, s71, 0
	s_add_u32 s76, s70, 0x2a000000
	v_writelane_b32 v252, s6, 35
	s_addc_u32 s77, s71, 0
	s_and_b64 s[0:1], s[0:1], s[84:85]
	v_writelane_b32 v252, s2, 37
	s_andn2_b64 vcc, exec, s[0:1]
	v_lshlrev_b32_e32 v226, 2, v0
	v_writelane_b32 v252, s3, 38
	s_cbranch_vccnz .LBB0_286
	s_add_u32 s12, s70, 0x800000
	s_addc_u32 s13, s71, 0
	v_readlane_b32 s28, v252, 22
	v_readlane_b32 s29, v252, 23
	v_readlane_b32 s30, v252, 24
	v_readlane_b32 s31, v252, 25
	v_and_b32_e32 v2, 3, v0
	v_lshlrev_b32_e32 v4, 1, v0
	v_and_b32_e32 v10, 0x78, v4
	v_or_b32_e32 v10, v10, v2
	v_lshrrev_b32_e32 v3, 6, v0
	v_mul_u32_u24_e32 v7, 0xab, v3
	v_lshrrev_b32_e32 v7, 9, v7
	v_mul_u32_u24_e32 v8, 3, v7
	v_sub_u32_e32 v8, v3, v8
	v_lshlrev_b32_e32 v7, 8, v7
	v_add_u32_e32 v7, 0x200, v7
	v_lshrrev_b32_e32 v9, 1, v8
	v_lshlrev_b32_e32 v9, 7, v9
	v_and_b32_e32 v8, 1, v8
	v_lshlrev_b32_e32 v8, 2, v8
	v_add3_u32 v7, v7, v9, v8
	v_add_lshl_u32 v7, v7, v10, 2
	global_load_dword v12, v7, s[12:13]
	v_add_u32_e32 v6, 8, v3
	v_mul_u32_u24_e32 v7, 0xab, v6
	v_lshrrev_b32_e32 v7, 9, v7
	v_mul_u32_u24_e32 v8, 3, v7
	v_sub_u32_e32 v8, v6, v8
	v_lshlrev_b32_e32 v7, 8, v7
	v_add_u32_e32 v7, 0x200, v7
	v_lshrrev_b32_e32 v9, 1, v8
	v_lshlrev_b32_e32 v9, 7, v9
	v_and_b32_e32 v8, 1, v8
	v_lshlrev_b32_e32 v8, 2, v8
	v_add3_u32 v7, v7, v9, v8
	v_add_lshl_u32 v7, v7, v10, 2
	global_load_dword v13, v7, s[12:13]
	v_add_u32_e32 v6, 16, v3
	v_mul_u32_u24_e32 v7, 0xab, v6
	v_lshrrev_b32_e32 v7, 9, v7
	v_mul_u32_u24_e32 v8, 3, v7
	v_sub_u32_e32 v8, v6, v8
	v_lshlrev_b32_e32 v7, 8, v7
	v_add_u32_e32 v7, 0x200, v7
	v_lshrrev_b32_e32 v9, 1, v8
	v_lshlrev_b32_e32 v9, 7, v9
	v_and_b32_e32 v8, 1, v8
	v_lshlrev_b32_e32 v8, 2, v8
	v_add3_u32 v7, v7, v9, v8
	v_add_lshl_u32 v7, v7, v10, 2
	global_load_dword v14, v7, s[12:13]
	v_add_u32_e32 v6, 24, v3
	v_mul_u32_u24_e32 v7, 0xab, v6
	v_lshrrev_b32_e32 v7, 9, v7
	v_mul_u32_u24_e32 v8, 3, v7
	v_sub_u32_e32 v8, v6, v8
	v_lshlrev_b32_e32 v7, 8, v7
	v_add_u32_e32 v7, 0x200, v7
	v_lshrrev_b32_e32 v9, 1, v8
	v_lshlrev_b32_e32 v9, 7, v9
	v_and_b32_e32 v8, 1, v8
	v_lshlrev_b32_e32 v8, 2, v8
	v_add3_u32 v7, v7, v9, v8
	v_add_lshl_u32 v7, v7, v10, 2
	global_load_dword v15, v7, s[12:13]
	v_add_u32_e32 v6, 32, v3
	v_mul_u32_u24_e32 v7, 0xab, v6
	v_lshrrev_b32_e32 v7, 9, v7
	v_mul_u32_u24_e32 v8, 3, v7
	v_sub_u32_e32 v8, v6, v8
	v_lshlrev_b32_e32 v7, 8, v7
	v_add_u32_e32 v7, 0x200, v7
	v_lshrrev_b32_e32 v9, 1, v8
	v_lshlrev_b32_e32 v9, 7, v9
	v_and_b32_e32 v8, 1, v8
	v_lshlrev_b32_e32 v8, 2, v8
	v_add3_u32 v7, v7, v9, v8
	v_add_lshl_u32 v7, v7, v10, 2
	global_load_dword v16, v7, s[12:13]
	v_add_u32_e32 v6, 40, v3
	v_mul_u32_u24_e32 v7, 0xab, v6
	v_lshrrev_b32_e32 v7, 9, v7
	v_mul_u32_u24_e32 v8, 3, v7
	v_sub_u32_e32 v8, v6, v8
	v_lshlrev_b32_e32 v7, 8, v7
	v_add_u32_e32 v7, 0x200, v7
	v_lshrrev_b32_e32 v9, 1, v8
	v_lshlrev_b32_e32 v9, 7, v9
	v_and_b32_e32 v8, 1, v8
	v_lshlrev_b32_e32 v8, 2, v8
	v_add3_u32 v7, v7, v9, v8
	v_add_lshl_u32 v7, v7, v10, 2
	global_load_dword v17, v7, s[12:13]
	v_add_u32_e32 v8, 0x1000, v226
	v_add_u32_e32 v9, 0x2000, v226
	global_load_dword v18, v226, s[28:29]
	global_load_dword v19, v226, s[28:29] offset:2048
	global_load_dword v20, v8, s[28:29]
	global_load_dword v21, v8, s[28:29] offset:2048
	global_load_dword v22, v9, s[28:29]
	global_load_dword v23, v9, s[28:29] offset:2048
	global_load_dword v24, v226, s[30:31]
	global_load_dword v25, v226, s[30:31] offset:2048
	v_add_u32_e32 v5, 0x20100, v226
	s_waitcnt vmcnt(0)
	ds_write_b32 v5, v12
	ds_write_b32 v5, v13 offset:2048
	ds_write_b32 v5, v14 offset:4096
	ds_write_b32 v5, v15 offset:6144
	ds_write_b32 v5, v16 offset:8192
	ds_write_b32 v5, v17 offset:10240
	ds_write_b32 v5, v18 offset:12288
	ds_write_b32 v5, v19 offset:14336
	ds_write_b32 v5, v20 offset:16384
	ds_write_b32 v5, v21 offset:18432
	ds_write_b32 v5, v22 offset:20480
	ds_write_b32 v5, v23 offset:22528
	ds_write_b32 v5, v24 offset:24576
	ds_write_b32 v5, v25 offset:26624
	s_cmpk_lt_i32 s95, 0x1200
	s_cselect_b64 s[2:3], -1, 0
	s_cmpk_gt_i32 s95, 0x11ff
	v_readfirstlane_b32 s4, v0
	s_waitcnt lgkmcnt(0)
	s_barrier
	s_cbranch_scc1 .LBB0_212
	s_ashr_i32 s5, s95, 31
	s_lshr_b32 s5, s5, 29
	s_add_i32 s5, s95, s5
	s_ashr_i32 s6, s5, 3
	s_and_b32 s5, s5, -8
	s_sub_i32 s5, s95, s5
	s_cmp_lt_i32 s5, 0
	s_movk_i32 s7, 0x241
	s_cselect_b32 s7, s7, 0x240
	s_mul_i32 s5, s5, s7
	s_add_i32 s5, s5, s6
	s_mul_hi_i32 s6, s5, 0x38e38e39
	s_lshr_b32 s7, s6, 31
	s_ashr_i32 s6, s6, 5
	s_add_i32 s6, s6, s7
	s_lshl_b32 s7, s6, 3
	s_mulk_i32 s6, 0x90
	s_sub_i32 s5, s5, s6
	s_bfe_u32 s6, s5, 0x3001c
	s_add_i32 s6, s5, s6
	s_sext_i32_i16 s8, s6
	s_and_b32 s6, s6, 0xfff8
	s_sub_i32 s5, s5, s6
	s_sext_i32_i16 s5, s5
	s_add_i32 s56, s7, s5
	s_ashr_i32 s55, s8, 3
